# attention queue: queue-index atomic result consumed at the end of the unit (wave 0 no longer stalls a round trip before issuing its loads)
# baseline (speedup 1.0000x reference)
.LBB0_989:
	s_mov_b32 s36, s6
	v_mov_b32_e32 v120, 0
	s_and_saveexec_b64 s[24:25], s[20:21]
	s_cbranch_execz .LBB0_993
	s_mov_b64 s[28:29], exec
	v_mbcnt_lo_u32_b32 v0, s28, 0
	v_mbcnt_hi_u32_b32 v0, s29, v0
	v_cmp_eq_u32_e32 vcc, 0, v0
	s_and_saveexec_b64 s[26:27], vcc
	s_cbranch_execz .LBB0_992
	s_bcnt1_i32_b64 s6, s[28:29]
	v_readlane_b32 s28, v232, 22
	v_mov_b32_e32 v1, s6
	v_readlane_b32 s29, v232, 23
	s_nop 4
	global_atomic_add v228, v3, v1, s[28:29] sc0
.LBB0_992:
	s_or_b64 exec, exec, s[26:27]
.LBB0_993:
	s_or_b64 exec, exec, s[24:25]
	s_cmpk_gt_i32 s36, 0x5ff
	s_cselect_b64 s[24:25], -1, 0
	s_and_b64 vcc, exec, s[24:25]
	s_cbranch_vccnz .LBB0_1003
	s_ashr_i32 s27, s36, 8
	s_mul_hi_i32 s28, s27, 0x55555556
	s_lshr_b32 s29, s28, 31
	s_ashr_i32 s6, s36, 6
	s_add_i32 s28, s28, s29
	s_mul_i32 s28, s28, 3
	s_mul_hi_i32 s6, s6, 0x2aaaaaab
	s_sub_i32 s27, s27, s28
	s_lshr_b32 s28, s6, 31
	s_ashr_i32 s6, s6, 1
	s_add_i32 s28, s6, s28
	s_lshl_b32 s6, s27, 1
	s_lshr_b32 s29, 64, s6
	s_and_b32 s26, s36, 63
	s_sub_i32 s30, 6, s6
	s_add_i32 s29, s29, -1
	s_lshr_b32 s37, s26, s30
	s_and_b32 s30, s29, s26
	s_lshl_b32 s40, s30, 7
	v_add_u32_e32 v0, s40, v85
	v_lshlrev_b32_e32 v0, s6, v0
	s_ashr_i32 s29, s28, 31
	v_add_u32_e32 v0, s37, v0
	v_readlane_b32 s30, v233, 14
	s_lshl_b32 s26, s27, 8
	s_and_b32 s27, s36, 0xc0
	s_lshl_b64 s[28:29], s[28:29], 13
	v_ashrrev_i32_e32 v1, 31, v0
	v_readlane_b32 s31, v233, 15
	s_or_b32 s26, s26, s27
	v_lshl_add_u64 v[0:1], s[28:29], 0, v[0:1]
	v_mov_b64_e32 v[4:5], s[30:31]
	s_ashr_i32 s27, s26, 31
	v_mad_u64_u32 v[6:7], s[30:31], v0, s33, v[4:5]
	v_mad_i32_i24 v7, v1, s33, v7
	s_lshl_b64 s[30:31], s[26:27], 1
	v_lshl_add_u64 v[0:1], v[6:7], 0, s[30:31]
	v_add_u32_e32 v6, s40, v88
	v_lshlrev_b32_e32 v6, s6, v6
	v_add_u32_e32 v6, s37, v6
	v_lshlrev_b32_e32 v2, 1, v84
	v_ashrrev_i32_e32 v7, 31, v6
	v_lshl_add_u64 v[0:1], v[0:1], 0, v[2:3]
	s_movk_i32 s38, 0x1000
	v_lshl_add_u64 v[6:7], s[28:29], 0, v[6:7]
	v_add_co_u32_e32 v0, vcc, s38, v0
	v_mad_u64_u32 v[4:5], s[38:39], v6, s33, v[4:5]
	v_mad_i32_i24 v5, v7, s33, v5
	v_lshl_add_u64 v[4:5], v[4:5], 0, s[30:31]
	v_addc_co_u32_e32 v1, vcc, 0, v1, vcc
	v_lshl_add_u64 v[4:5], v[4:5], 0, v[2:3]
	v_add_co_u32_e32 v8, vcc, 0x1000, v4
	s_add_i32 s38, s40, 0xffffff80
	s_nop 0
	v_addc_co_u32_e32 v9, vcc, 0, v5, vcc
	global_load_dwordx4 v[4:7], v[0:1], off offset:2560
	s_nop 0
	global_load_dwordx4 v[8:11], v[8:9], off offset:2560
	v_add_u32_e32 v0, s38, v85
	v_lshlrev_b32_e32 v0, s6, v0
	v_add_u32_e32 v0, s37, v0
	v_cmp_lt_i32_e32 vcc, -1, v0
	v_mov_b32_e32 v16, 0
	v_mov_b32_e32 v20, 0
	v_mov_b32_e32 v21, 0
	v_mov_b32_e32 v22, 0
	v_mov_b32_e32 v23, 0
	v_mov_b32_e32 v12, 0
	v_mov_b32_e32 v13, 0
	v_mov_b32_e32 v14, 0
	v_mov_b32_e32 v15, 0
	s_and_saveexec_b64 s[30:31], vcc
	s_cbranch_execz .LBB0_996
	v_readlane_b32 s40, v233, 14
	v_mov_b32_e32 v1, v3
	v_readlane_b32 s41, v233, 15
	v_lshl_add_u64 v[0:1], s[28:29], 0, v[0:1]
	s_nop 0
	v_mov_b64_e32 v[12:13], s[40:41]
	v_mad_u64_u32 v[12:13], vcc, v0, s33, v[12:13]
	v_mad_i32_i24 v13, v1, s33, v13
	v_lshl_add_u64 v[0:1], s[26:27], 1, v[12:13]
	v_lshl_add_u64 v[0:1], v[0:1], 0, v[2:3]
	v_add_co_u32_e32 v0, vcc, 0x2000, v0
	s_nop 1
	v_addc_co_u32_e32 v1, vcc, 0, v1, vcc
	global_load_dwordx4 v[20:23], v[0:1], off
	global_load_dwordx4 v[12:15], v[0:1], off offset:1536

.LBB0_1005:
	s_or_b64 exec, exec, s[26:27]
	s_add_i32 s6, s34, 16
	s_and_saveexec_b64 s[26:27], s[20:21]
	v_readlane_b32 s40, v233, 6
	s_cbranch_execz .LBB0_988
	s_lshl_b32 s28, s6, 2
	s_add_i32 s28, s28, 0
	s_add_i32 s28, s28, 0x20140
	v_mov_b32_e32 v0, s28
	s_waitcnt vmcnt(4)
	v_mov_b32_e32 v120, v228
	ds_write_b32 v0, v120
	s_branch .LBB0_988
